# pass B MFMA chain split into two accumulators + staged lgkmcnt waits on the A-operand reads
# speedup vs baseline: 1.0205x; 1.0003x over previous
.Lpb2_cloop:
	s_waitcnt lgkmcnt(0)
	s_barrier
	v_add_u32_e32 v10, s18, v4
	ds_read_b128 v[20:23], v10
	ds_read_b128 v[24:27], v10 offset:16
	ds_read_b128 v[28:31], v10 offset:32
	ds_read_b128 v[32:35], v10 offset:48
	s_mul_i32 s19, s17, 16640
	s_add_i32 s19, s19, 38912
	v_add_u32_e32 v11, s19, v6
	s_lshl_b32 s20, s17, 12
	s_add_i32 s20, s20, 9216
	v_add_u32_e32 v12, s20, v7
	s_sub_i32 s21, 4352, s18
	v_add_u32_e32 v13, s21, v8
	s_waitcnt lgkmcnt(3)
	v_mfma_f32_16x16x4_f32 v[56:59], v20, v36, v[52:55]
	v_mfma_f32_16x16x4_f32 v[60:63], v21, v37, 0
	ds_read_b32 v36, v11 offset:0
	v_mfma_f32_16x16x4_f32 v[56:59], v22, v38, v[56:59]
	ds_read_b32 v37, v11 offset:256
	v_mfma_f32_16x16x4_f32 v[60:63], v23, v39, v[60:63]
	ds_read_b32 v38, v11 offset:512
	s_waitcnt lgkmcnt(5)
	v_mfma_f32_16x16x4_f32 v[56:59], v24, v40, v[56:59]
	ds_read_b32 v39, v11 offset:768
	v_mfma_f32_16x16x4_f32 v[60:63], v25, v41, v[60:63]
	ds_read_b32 v40, v11 offset:1040
	v_mfma_f32_16x16x4_f32 v[56:59], v26, v42, v[56:59]
	ds_read_b32 v41, v11 offset:1296
	v_mfma_f32_16x16x4_f32 v[60:63], v27, v43, v[60:63]
	ds_read_b32 v42, v11 offset:1552
	s_waitcnt lgkmcnt(8)
	v_mfma_f32_16x16x4_f32 v[56:59], v28, v44, v[56:59]
	ds_read_b32 v43, v11 offset:1808
	v_mfma_f32_16x16x4_f32 v[60:63], v29, v45, v[60:63]
	ds_read_b32 v44, v11 offset:2080
	v_mfma_f32_16x16x4_f32 v[56:59], v30, v46, v[56:59]
	ds_read_b32 v45, v11 offset:2336
	v_mfma_f32_16x16x4_f32 v[60:63], v31, v47, v[60:63]
	ds_read_b32 v46, v11 offset:2592
	s_waitcnt lgkmcnt(11)
	v_mfma_f32_16x16x4_f32 v[56:59], v32, v48, v[56:59]
	ds_read_b32 v47, v11 offset:2848
	v_mfma_f32_16x16x4_f32 v[60:63], v33, v49, v[60:63]
	ds_read_b32 v48, v11 offset:3120
	v_mfma_f32_16x16x4_f32 v[56:59], v34, v50, v[56:59]
	ds_read_b32 v49, v11 offset:3376
	v_mfma_f32_16x16x4_f32 v[60:63], v35, v51, v[60:63]
	ds_read_b32 v50, v11 offset:3632
	ds_read_b32 v51, v11 offset:3888
	ds_read2st64_b32 v[52:53], v12 offset1:1
	ds_read2st64_b32 v[54:55], v12 offset0:2 offset1:3
	s_nop 7
	v_pk_add_f32 v[56:57], v[56:57], v[60:61]
	v_pk_add_f32 v[58:59], v[58:59], v[62:63]
	ds_write_b32 v13, v56
	ds_write_b32 v13, v57 offset:272
	ds_write_b32 v13, v58 offset:544
	ds_write_b32 v13, v59 offset:816
	global_store_dword v9, v56, s[12:13]
	global_store_dword v9, v57, s[12:13] offset:256
	global_store_dword v9, v58, s[12:13] offset:512
	global_store_dword v9, v59, s[12:13] offset:768
	s_mov_b32 s18, s21
	s_add_u32 s12, s12, 0x8000
	s_addc_u32 s13, s13, 0
	s_add_i32 s17, s17, 1
	s_cmp_eq_u32 s17, 7
	s_cselect_b32 s17, 0, s17
	s_add_i32 s16, s16, 1
	s_cmp_eq_u32 s16, 79
	s_cbranch_scc0 .Lpb2_cloop
	s_waitcnt vmcnt(0) lgkmcnt(0)
	s_branch .LBB0_594
